# P2 residual epilogue: base loads prefetched three row-groups ahead, 16-byte stores via permlane16 swap, counted waits
# speedup vs baseline: 1.0226x; 1.0044x over previous
.LBB0_237:
	s_ashr_i32 s39, s38, 31
	s_lshl_b64 s[2:3], s[38:39], 8
	v_lshl_or_b32 v144, s0, 8, v148
	v_lshl_add_u64 v[146:147], s[2:3], 0, v[134:135]
	v_ashrrev_i32_e32 v145, 31, v144
	v_lshlrev_b64 v[154:155], 10, v[146:147]
	v_lshl_add_u64 v[158:159], v[154:155], 0, v[144:145]
	v_lshl_add_u64 v[160:161], v[158:159], 2, s[18:19]
	v_add_co_u32_e32 v224, vcc, 0x10000, v160
	s_nop 1
	v_addc_co_u32_e32 v225, vcc, 0, v161, vcc
	v_add_co_u32_e32 v226, vcc, 0x20000, v160
	s_nop 1
	v_addc_co_u32_e32 v227, vcc, 0, v161, vcc
	v_add_co_u32_e32 v228, vcc, 0x30000, v160
	s_nop 1
	v_addc_co_u32_e32 v229, vcc, 0, v161, vcc
	v_add_co_u32_e32 v230, vcc, 0x80000, v160
	s_nop 1
	v_addc_co_u32_e32 v231, vcc, 0, v161, vcc
	v_add_co_u32_e32 v232, vcc, 0x90000, v160
	s_nop 1
	v_addc_co_u32_e32 v233, vcc, 0, v161, vcc
	v_add_co_u32_e32 v234, vcc, 0xa0000, v160
	s_nop 1
	v_addc_co_u32_e32 v235, vcc, 0, v161, vcc
	v_add_co_u32_e32 v236, vcc, 0xb0000, v160
	s_nop 1
	v_addc_co_u32_e32 v237, vcc, 0, v161, vcc
	global_load_dwordx4 v[166:169], v[160:161], off
	global_load_dwordx4 v[170:173], v[160:161], off offset:64
	global_load_dwordx4 v[174:177], v[160:161], off offset:512
	global_load_dwordx4 v[178:181], v[160:161], off offset:576
	global_load_dwordx4 v[182:185], v[224:225], off
	global_load_dwordx4 v[186:189], v[224:225], off offset:64
	global_load_dwordx4 v[190:193], v[224:225], off offset:512
	global_load_dwordx4 v[194:197], v[224:225], off offset:576
	global_load_dwordx4 v[198:201], v[226:227], off
	global_load_dwordx4 v[202:205], v[226:227], off offset:64
	global_load_dwordx4 v[206:209], v[226:227], off offset:512
	global_load_dwordx4 v[210:213], v[226:227], off offset:576
	v_and_b32_e32 v248, 16, v0
	v_lshrrev_b32_e32 v249, 1, v248
	v_add_u32_e32 v248, v248, v249
	v_mov_b32_e32 v249, 0
	s_waitcnt vmcnt(11)
	v_lshlrev_b64 v[158:159], 1, v[158:159]
	v_lshl_add_u64 v[162:163], s[14:15], 0, v[158:159]
	v_xor_b32_e32 v153, 32, v152
	s_lshl_b32 s38, s0, 2
	s_ashr_i32 s39, s38, 31
	v_pk_fma_f32 v[156:157], v[128:129], 0.5, v[168:169] op_sel_hi:[1,0,1]
	v_pk_fma_f32 v[154:155], v[126:127], 0.5, v[166:167] op_sel_hi:[1,0,1]
	s_nop 0
	v_cvt_pk_bf16_f32 v240, v154, v155
	v_cvt_pk_bf16_f32 v241, v156, v157
	s_waitcnt vmcnt(10)
	v_or_b32_e32 v162, 32, v158
	v_mov_b32_e32 v163, v159
	v_lshl_add_u64 v[162:163], s[14:15], 0, v[162:163]
	v_mul_f32_e32 v155, v155, v155
	v_mul_f32_e32 v157, v157, v157
	v_fmac_f32_e32 v155, v154, v154
	v_fmac_f32_e32 v157, v156, v156
	v_add_f32_e32 v154, v155, v157
	v_pk_fma_f32 v[128:129], v[124:125], 0.5, v[172:173] op_sel_hi:[1,0,1]
	v_pk_fma_f32 v[126:127], v[122:123], 0.5, v[170:171] op_sel_hi:[1,0,1]
	s_nop 0
	v_cvt_pk_bf16_f32 v242, v126, v127
	v_cvt_pk_bf16_f32 v243, v128, v129
	s_nop 1
	v_permlane16_swap_b32_e32 v240, v242
	v_permlane16_swap_b32_e32 v241, v243
	v_lshl_add_u64 v[250:251], v[162:163], 0, v[248:249]
	global_store_dwordx4 v[250:251], v[240:243], off offset:-32
	s_waitcnt vmcnt(10)
	v_or_b32_e32 v162, 0x100, v158
	v_mov_b32_e32 v163, v159
	v_lshl_add_u64 v[162:163], s[14:15], 0, v[162:163]
	v_mul_f32_e32 v127, v127, v127
	v_mul_f32_e32 v129, v129, v129
	v_fmac_f32_e32 v127, v126, v126
	v_fmac_f32_e32 v129, v128, v128
	v_add_f32_e32 v126, v127, v129
	v_add_f32_e32 v126, v154, v126
	v_or_b32_e32 v158, 0x120, v158
	v_pk_fma_f32 v[124:125], v[120:121], 0.5, v[176:177] op_sel_hi:[1,0,1]
	v_pk_fma_f32 v[164:165], v[118:119], 0.5, v[174:175] op_sel_hi:[1,0,1]
	s_nop 0
	v_cvt_pk_bf16_f32 v244, v164, v165
	v_cvt_pk_bf16_f32 v245, v124, v125
	s_waitcnt vmcnt(9)
	v_and_b32_e32 v119, 64, v152
	v_mul_f32_e32 v127, v165, v165
	v_mul_f32_e32 v125, v125, v125
	v_xor_b32_e32 v118, 16, v152
	v_add_u32_e32 v119, 64, v119
	v_fmac_f32_e32 v127, v164, v164
	v_fmac_f32_e32 v125, v124, v124
	v_cmp_lt_i32_e32 vcc, v118, v119
	v_add_f32_e32 v124, v127, v125
	v_add_f32_e32 v124, v126, v124
	v_cndmask_b32_e32 v118, v152, v118, vcc
	v_lshlrev_b32_e32 v118, 2, v118
	v_cmp_lt_i32_e32 vcc, v153, v119
	v_pk_fma_f32 v[122:123], v[116:117], 0.5, v[180:181] op_sel_hi:[1,0,1]
	v_pk_fma_f32 v[114:115], v[114:115], 0.5, v[178:179] op_sel_hi:[1,0,1]
	global_load_dwordx4 v[166:169], v[228:229], off
	global_load_dwordx4 v[170:173], v[228:229], off offset:64
	global_load_dwordx4 v[174:177], v[228:229], off offset:512
	global_load_dwordx4 v[178:181], v[228:229], off offset:576
	v_mul_f32_e32 v117, v123, v123
	v_mul_f32_e32 v116, v115, v115
	v_fmac_f32_e32 v116, v114, v114
	v_fmac_f32_e32 v117, v122, v122
	v_add_f32_e32 v116, v116, v117
	v_add_f32_e32 v116, v124, v116
	ds_bpermute_b32 v117, v118, v116
	v_cndmask_b32_e32 v119, v152, v153, vcc
	v_cvt_pk_bf16_f32 v246, v114, v115
	v_cvt_pk_bf16_f32 v247, v122, v123
	v_lshl_add_u64 v[122:123], s[14:15], 0, v[158:159]
	s_waitcnt lgkmcnt(0)
	v_add_f32_e32 v114, v116, v117
	v_lshlrev_b32_e32 v116, 2, v119
	ds_bpermute_b32 v115, v116, v114
	s_nop 1
	v_permlane16_swap_b32_e32 v244, v246
	v_permlane16_swap_b32_e32 v245, v247
	v_lshl_add_u64 v[250:251], v[122:123], 0, v[248:249]
	global_store_dwordx4 v[250:251], v[244:247], off offset:-32
	s_and_saveexec_b64 s[46:47], s[4:5]
	s_cbranch_execz .LBB0_239
	v_lshlrev_b64 v[120:121], 6, v[146:147]
	v_lshl_add_u64 v[120:121], s[16:17], 0, v[120:121]
	v_lshl_add_u64 v[120:121], s[38:39], 2, v[120:121]
	s_lshl_b32 s26, s59, 2
	v_lshl_add_u64 v[120:121], v[120:121], 0, s[26:27]
	s_waitcnt lgkmcnt(0)
	v_add_f32_e32 v114, v114, v115
	global_store_dword v[120:121], v114, off
.LBB0_239:
	s_or_b64 exec, exec, s[46:47]
	v_or_b32_e32 v114, 16, v146
	s_waitcnt lgkmcnt(0)
	v_mov_b32_e32 v115, v147
	v_lshlrev_b64 v[120:121], 10, v[114:115]
	v_lshl_add_u64 v[124:125], v[120:121], 0, v[144:145]
	v_lshl_add_u64 v[126:127], v[124:125], 2, s[18:19]
	s_waitcnt vmcnt(13)
	v_lshlrev_b64 v[124:125], 1, v[124:125]
	v_lshl_add_u64 v[128:129], s[14:15], 0, v[124:125]
	v_pk_fma_f32 v[122:123], v[112:113], 0.5, v[184:185] op_sel_hi:[1,0,1]
	v_pk_fma_f32 v[120:121], v[110:111], 0.5, v[182:183] op_sel_hi:[1,0,1]
	v_mul_f32_e32 v119, v123, v123
	v_cvt_pk_bf16_f32 v240, v120, v121
	v_cvt_pk_bf16_f32 v241, v122, v123
	s_waitcnt vmcnt(12)
	v_or_b32_e32 v128, 32, v124
	v_mov_b32_e32 v129, v125
	v_lshl_add_u64 v[128:129], s[14:15], 0, v[128:129]
	v_mul_f32_e32 v117, v121, v121
	v_fmac_f32_e32 v117, v120, v120
	v_fmac_f32_e32 v119, v122, v122
	v_add_f32_e32 v117, v117, v119
	v_pk_fma_f32 v[112:113], v[108:109], 0.5, v[188:189] op_sel_hi:[1,0,1]
	v_pk_fma_f32 v[110:111], v[106:107], 0.5, v[186:187] op_sel_hi:[1,0,1]
	s_nop 0
	v_cvt_pk_bf16_f32 v242, v110, v111
	v_cvt_pk_bf16_f32 v243, v112, v113
	s_nop 1
	v_permlane16_swap_b32_e32 v240, v242
	v_permlane16_swap_b32_e32 v241, v243
	v_lshl_add_u64 v[250:251], v[128:129], 0, v[248:249]
	global_store_dwordx4 v[250:251], v[240:243], off offset:-32
	s_waitcnt vmcnt(12)
	v_or_b32_e32 v128, 0x100, v124
	v_mov_b32_e32 v129, v125
	v_lshl_add_u64 v[128:129], s[14:15], 0, v[128:129]
	v_mul_f32_e32 v111, v111, v111
	v_mul_f32_e32 v113, v113, v113
	v_fmac_f32_e32 v111, v110, v110
	v_fmac_f32_e32 v113, v112, v112
	v_add_f32_e32 v110, v111, v113
	v_add_f32_e32 v110, v117, v110
	v_or_b32_e32 v124, 0x120, v124
	v_pk_fma_f32 v[108:109], v[104:105], 0.5, v[192:193] op_sel_hi:[1,0,1]
	v_pk_fma_f32 v[106:107], v[102:103], 0.5, v[190:191] op_sel_hi:[1,0,1]
	s_nop 0
	v_cvt_pk_bf16_f32 v244, v106, v107
	v_cvt_pk_bf16_f32 v245, v108, v109
	s_waitcnt vmcnt(11)
	v_mul_f32_e32 v107, v107, v107
	v_mul_f32_e32 v109, v109, v109
	v_fmac_f32_e32 v107, v106, v106
	v_fmac_f32_e32 v109, v108, v108
	v_add_f32_e32 v106, v107, v109
	v_add_f32_e32 v106, v110, v106
	v_pk_fma_f32 v[100:101], v[100:101], 0.5, v[196:197] op_sel_hi:[1,0,1]
	v_pk_fma_f32 v[98:99], v[98:99], 0.5, v[194:195] op_sel_hi:[1,0,1]
	global_load_dwordx4 v[182:185], v[230:231], off
	global_load_dwordx4 v[186:189], v[230:231], off offset:64
	global_load_dwordx4 v[190:193], v[230:231], off offset:512
	global_load_dwordx4 v[194:197], v[230:231], off offset:576
	v_mul_f32_e32 v103, v101, v101
	v_mul_f32_e32 v102, v99, v99
	v_fmac_f32_e32 v102, v98, v98
	v_fmac_f32_e32 v103, v100, v100
	v_add_f32_e32 v102, v102, v103
	v_add_f32_e32 v103, v106, v102
	ds_bpermute_b32 v104, v118, v103
	v_cvt_pk_bf16_f32 v246, v98, v99
	s_waitcnt lgkmcnt(0)
	v_add_f32_e32 v98, v103, v104
	ds_bpermute_b32 v99, v116, v98
	v_cvt_pk_bf16_f32 v247, v100, v101
	v_lshl_add_u64 v[100:101], s[14:15], 0, v[124:125]
	s_nop 1
	v_permlane16_swap_b32_e32 v244, v246
	v_permlane16_swap_b32_e32 v245, v247
	v_lshl_add_u64 v[250:251], v[100:101], 0, v[248:249]
	global_store_dwordx4 v[250:251], v[244:247], off offset:-32
	s_and_saveexec_b64 s[46:47], s[4:5]
	s_cbranch_execz .LBB0_241
	v_lshlrev_b64 v[100:101], 6, v[114:115]
	v_lshl_add_u64 v[100:101], s[16:17], 0, v[100:101]
	v_lshl_add_u64 v[100:101], s[38:39], 2, v[100:101]
	s_lshl_b32 s26, s59, 2
	v_lshl_add_u64 v[100:101], v[100:101], 0, s[26:27]
	s_waitcnt lgkmcnt(0)
	v_add_f32_e32 v98, v98, v99
	global_store_dword v[100:101], v98, off
.LBB0_241:
	s_or_b64 exec, exec, s[46:47]
	v_or_b32_e32 v98, 32, v146
	s_waitcnt lgkmcnt(0)
	v_mov_b32_e32 v99, v147
	v_lshlrev_b64 v[100:101], 10, v[98:99]
	v_lshl_add_u64 v[104:105], v[100:101], 0, v[144:145]
	v_lshl_add_u64 v[106:107], v[104:105], 2, s[18:19]
	s_waitcnt vmcnt(15)
	v_lshlrev_b64 v[104:105], 1, v[104:105]
	v_lshl_add_u64 v[108:109], s[14:15], 0, v[104:105]
	v_pk_fma_f32 v[102:103], v[96:97], 0.5, v[200:201] op_sel_hi:[1,0,1]
	v_pk_fma_f32 v[100:101], v[94:95], 0.5, v[198:199] op_sel_hi:[1,0,1]
	s_nop 0
	v_cvt_pk_bf16_f32 v240, v100, v101
	v_cvt_pk_bf16_f32 v241, v102, v103
	s_waitcnt vmcnt(14)
	v_or_b32_e32 v108, 32, v104
	v_mov_b32_e32 v109, v105
	v_lshl_add_u64 v[108:109], s[14:15], 0, v[108:109]
	v_mul_f32_e32 v101, v101, v101
	v_mul_f32_e32 v103, v103, v103
	v_fmac_f32_e32 v101, v100, v100
	v_fmac_f32_e32 v103, v102, v102
	v_add_f32_e32 v100, v101, v103
	v_pk_fma_f32 v[96:97], v[92:93], 0.5, v[204:205] op_sel_hi:[1,0,1]
	v_pk_fma_f32 v[94:95], v[90:91], 0.5, v[202:203] op_sel_hi:[1,0,1]
	s_nop 0
	v_cvt_pk_bf16_f32 v242, v94, v95
	v_cvt_pk_bf16_f32 v243, v96, v97
	s_nop 1
	v_permlane16_swap_b32_e32 v240, v242
	v_permlane16_swap_b32_e32 v241, v243
	v_lshl_add_u64 v[250:251], v[108:109], 0, v[248:249]
	global_store_dwordx4 v[250:251], v[240:243], off offset:-32
	s_waitcnt vmcnt(14)
	v_or_b32_e32 v108, 0x100, v104
	v_mov_b32_e32 v109, v105
	v_lshl_add_u64 v[108:109], s[14:15], 0, v[108:109]
	v_mul_f32_e32 v95, v95, v95
	v_mul_f32_e32 v97, v97, v97
	v_fmac_f32_e32 v95, v94, v94
	v_fmac_f32_e32 v97, v96, v96
	v_add_f32_e32 v94, v95, v97
	v_add_f32_e32 v94, v100, v94
	v_or_b32_e32 v104, 0x120, v104
	v_pk_fma_f32 v[92:93], v[88:89], 0.5, v[208:209] op_sel_hi:[1,0,1]
	v_pk_fma_f32 v[90:91], v[86:87], 0.5, v[206:207] op_sel_hi:[1,0,1]
	s_nop 0
	v_cvt_pk_bf16_f32 v244, v90, v91
	v_cvt_pk_bf16_f32 v245, v92, v93
	s_waitcnt vmcnt(13)
	v_mul_f32_e32 v91, v91, v91
	v_mul_f32_e32 v93, v93, v93
	v_fmac_f32_e32 v91, v90, v90
	v_fmac_f32_e32 v93, v92, v92
	v_add_f32_e32 v90, v91, v93
	v_add_f32_e32 v90, v94, v90
	v_pk_fma_f32 v[84:85], v[84:85], 0.5, v[212:213] op_sel_hi:[1,0,1]
	v_pk_fma_f32 v[82:83], v[82:83], 0.5, v[210:211] op_sel_hi:[1,0,1]
	global_load_dwordx4 v[198:201], v[232:233], off
	global_load_dwordx4 v[202:205], v[232:233], off offset:64
	global_load_dwordx4 v[206:209], v[232:233], off offset:512
	global_load_dwordx4 v[210:213], v[232:233], off offset:576
	v_mul_f32_e32 v87, v85, v85
	v_mul_f32_e32 v86, v83, v83
	v_fmac_f32_e32 v86, v82, v82
	v_fmac_f32_e32 v87, v84, v84
	v_add_f32_e32 v86, v86, v87
	v_add_f32_e32 v87, v90, v86
	ds_bpermute_b32 v88, v118, v87
	v_cvt_pk_bf16_f32 v246, v82, v83
	s_waitcnt lgkmcnt(0)
	v_add_f32_e32 v82, v87, v88
	ds_bpermute_b32 v83, v116, v82
	v_cvt_pk_bf16_f32 v247, v84, v85
	v_lshl_add_u64 v[84:85], s[14:15], 0, v[104:105]
	s_nop 1
	v_permlane16_swap_b32_e32 v244, v246
	v_permlane16_swap_b32_e32 v245, v247
	v_lshl_add_u64 v[250:251], v[84:85], 0, v[248:249]
	global_store_dwordx4 v[250:251], v[244:247], off offset:-32
	s_and_saveexec_b64 s[46:47], s[4:5]
	s_cbranch_execz .LBB0_243
	v_lshlrev_b64 v[84:85], 6, v[98:99]
	v_lshl_add_u64 v[84:85], s[16:17], 0, v[84:85]
	v_lshl_add_u64 v[84:85], s[38:39], 2, v[84:85]
	s_lshl_b32 s26, s59, 2
	v_lshl_add_u64 v[84:85], v[84:85], 0, s[26:27]
	s_waitcnt lgkmcnt(0)
	v_add_f32_e32 v82, v82, v83
	global_store_dword v[84:85], v82, off
.LBB0_243:
	s_or_b64 exec, exec, s[46:47]
	v_or_b32_e32 v82, 48, v146
	s_waitcnt lgkmcnt(0)
	v_mov_b32_e32 v83, v147
	v_lshlrev_b64 v[84:85], 10, v[82:83]
	v_lshl_add_u64 v[88:89], v[84:85], 0, v[144:145]
	v_lshl_add_u64 v[90:91], v[88:89], 2, s[18:19]
	s_waitcnt vmcnt(16)
	v_lshlrev_b64 v[88:89], 1, v[88:89]
	v_lshl_add_u64 v[92:93], s[14:15], 0, v[88:89]
	v_pk_fma_f32 v[86:87], v[80:81], 0.5, v[168:169] op_sel_hi:[1,0,1]
	v_pk_fma_f32 v[84:85], v[78:79], 0.5, v[166:167] op_sel_hi:[1,0,1]
	s_nop 0
	v_cvt_pk_bf16_f32 v240, v84, v85
	v_cvt_pk_bf16_f32 v241, v86, v87
	s_waitcnt vmcnt(15)
	v_or_b32_e32 v92, 32, v88
	v_mov_b32_e32 v93, v89
	v_lshl_add_u64 v[92:93], s[14:15], 0, v[92:93]
	v_mul_f32_e32 v85, v85, v85
	v_mul_f32_e32 v87, v87, v87
	v_fmac_f32_e32 v85, v84, v84
	v_fmac_f32_e32 v87, v86, v86
	v_add_f32_e32 v84, v85, v87
	v_pk_fma_f32 v[80:81], v[76:77], 0.5, v[172:173] op_sel_hi:[1,0,1]
	v_pk_fma_f32 v[78:79], v[74:75], 0.5, v[170:171] op_sel_hi:[1,0,1]
	s_nop 0
	v_cvt_pk_bf16_f32 v242, v78, v79
	v_cvt_pk_bf16_f32 v243, v80, v81
	s_nop 1
	v_permlane16_swap_b32_e32 v240, v242
	v_permlane16_swap_b32_e32 v241, v243
	v_lshl_add_u64 v[250:251], v[92:93], 0, v[248:249]
	global_store_dwordx4 v[250:251], v[240:243], off offset:-32
	s_waitcnt vmcnt(15)
	v_or_b32_e32 v92, 0x100, v88
	v_mov_b32_e32 v93, v89
	v_lshl_add_u64 v[92:93], s[14:15], 0, v[92:93]
	v_mul_f32_e32 v79, v79, v79
	v_mul_f32_e32 v81, v81, v81
	v_fmac_f32_e32 v79, v78, v78
	v_fmac_f32_e32 v81, v80, v80
	v_add_f32_e32 v78, v79, v81
	v_add_f32_e32 v78, v84, v78
	v_or_b32_e32 v88, 0x120, v88
	v_pk_fma_f32 v[76:77], v[72:73], 0.5, v[176:177] op_sel_hi:[1,0,1]
	v_pk_fma_f32 v[74:75], v[70:71], 0.5, v[174:175] op_sel_hi:[1,0,1]
	s_nop 0
	v_cvt_pk_bf16_f32 v244, v74, v75
	v_cvt_pk_bf16_f32 v245, v76, v77
	s_waitcnt vmcnt(14)
	v_mul_f32_e32 v75, v75, v75
	v_mul_f32_e32 v77, v77, v77
	v_fmac_f32_e32 v75, v74, v74
	v_fmac_f32_e32 v77, v76, v76
	v_add_f32_e32 v74, v75, v77
	v_add_f32_e32 v74, v78, v74
	v_pk_fma_f32 v[68:69], v[68:69], 0.5, v[180:181] op_sel_hi:[1,0,1]
	v_pk_fma_f32 v[66:67], v[66:67], 0.5, v[178:179] op_sel_hi:[1,0,1]
	global_load_dwordx4 v[166:169], v[234:235], off
	global_load_dwordx4 v[170:173], v[234:235], off offset:64
	global_load_dwordx4 v[174:177], v[234:235], off offset:512
	global_load_dwordx4 v[178:181], v[234:235], off offset:576
	v_mul_f32_e32 v71, v69, v69
	v_mul_f32_e32 v70, v67, v67
	v_fmac_f32_e32 v70, v66, v66
	v_fmac_f32_e32 v71, v68, v68
	v_add_f32_e32 v70, v70, v71
	v_add_f32_e32 v71, v74, v70
	ds_bpermute_b32 v72, v118, v71
	v_cvt_pk_bf16_f32 v246, v66, v67
	s_waitcnt lgkmcnt(0)
	v_add_f32_e32 v66, v71, v72
	ds_bpermute_b32 v67, v116, v66
	v_cvt_pk_bf16_f32 v247, v68, v69
	v_lshl_add_u64 v[68:69], s[14:15], 0, v[88:89]
	s_nop 1
	v_permlane16_swap_b32_e32 v244, v246
	v_permlane16_swap_b32_e32 v245, v247
	v_lshl_add_u64 v[250:251], v[68:69], 0, v[248:249]
	global_store_dwordx4 v[250:251], v[244:247], off offset:-32
	s_and_saveexec_b64 s[46:47], s[4:5]
	s_cbranch_execz .LBB0_245
	v_lshlrev_b64 v[68:69], 6, v[82:83]
	v_lshl_add_u64 v[68:69], s[16:17], 0, v[68:69]
	v_lshl_add_u64 v[68:69], s[38:39], 2, v[68:69]
	s_lshl_b32 s26, s59, 2
	v_lshl_add_u64 v[68:69], v[68:69], 0, s[26:27]
	s_waitcnt lgkmcnt(0)
	v_add_f32_e32 v66, v66, v67
	global_store_dword v[68:69], v66, off
.LBB0_245:
	s_or_b64 exec, exec, s[46:47]
	s_waitcnt lgkmcnt(0)
	v_lshl_add_u64 v[66:67], v[146:147], 0, s[30:31]
	v_lshlrev_b64 v[68:69], 10, v[66:67]
	v_lshl_add_u64 v[72:73], v[68:69], 0, v[144:145]
	v_lshl_add_u64 v[74:75], v[72:73], 2, s[18:19]
	s_waitcnt vmcnt(16)
	v_lshlrev_b64 v[72:73], 1, v[72:73]
	v_lshl_add_u64 v[76:77], s[14:15], 0, v[72:73]
	v_pk_fma_f32 v[70:71], v[64:65], 0.5, v[184:185] op_sel_hi:[1,0,1]
	v_pk_fma_f32 v[68:69], v[62:63], 0.5, v[182:183] op_sel_hi:[1,0,1]
	s_nop 0
	v_cvt_pk_bf16_f32 v240, v68, v69
	v_cvt_pk_bf16_f32 v241, v70, v71
	s_waitcnt vmcnt(15)
	v_or_b32_e32 v76, 32, v72
	v_mov_b32_e32 v77, v73
	v_lshl_add_u64 v[76:77], s[14:15], 0, v[76:77]
	v_mul_f32_e32 v69, v69, v69
	v_mul_f32_e32 v71, v71, v71
	v_fmac_f32_e32 v69, v68, v68
	v_fmac_f32_e32 v71, v70, v70
	v_add_f32_e32 v68, v69, v71
	v_pk_fma_f32 v[64:65], v[60:61], 0.5, v[188:189] op_sel_hi:[1,0,1]
	v_pk_fma_f32 v[62:63], v[58:59], 0.5, v[186:187] op_sel_hi:[1,0,1]
	s_nop 0
	v_cvt_pk_bf16_f32 v242, v62, v63
	v_cvt_pk_bf16_f32 v243, v64, v65
	s_nop 1
	v_permlane16_swap_b32_e32 v240, v242
	v_permlane16_swap_b32_e32 v241, v243
	v_lshl_add_u64 v[250:251], v[76:77], 0, v[248:249]
	global_store_dwordx4 v[250:251], v[240:243], off offset:-32
	s_waitcnt vmcnt(15)
	v_or_b32_e32 v76, 0x100, v72
	v_mov_b32_e32 v77, v73
	v_lshl_add_u64 v[76:77], s[14:15], 0, v[76:77]
	v_mul_f32_e32 v63, v63, v63
	v_mul_f32_e32 v65, v65, v65
	v_fmac_f32_e32 v63, v62, v62
	v_fmac_f32_e32 v65, v64, v64
	v_add_f32_e32 v62, v63, v65
	v_add_f32_e32 v62, v68, v62
	v_or_b32_e32 v72, 0x120, v72
	v_pk_fma_f32 v[60:61], v[56:57], 0.5, v[192:193] op_sel_hi:[1,0,1]
	v_pk_fma_f32 v[58:59], v[54:55], 0.5, v[190:191] op_sel_hi:[1,0,1]
	s_nop 0
	v_cvt_pk_bf16_f32 v244, v58, v59
	v_cvt_pk_bf16_f32 v245, v60, v61
	s_waitcnt vmcnt(14)
	v_mul_f32_e32 v59, v59, v59
	v_mul_f32_e32 v61, v61, v61
	v_fmac_f32_e32 v59, v58, v58
	v_fmac_f32_e32 v61, v60, v60
	v_add_f32_e32 v58, v59, v61
	v_add_f32_e32 v58, v62, v58
	v_pk_fma_f32 v[52:53], v[52:53], 0.5, v[196:197] op_sel_hi:[1,0,1]
	v_pk_fma_f32 v[50:51], v[50:51], 0.5, v[194:195] op_sel_hi:[1,0,1]
	global_load_dwordx4 v[182:185], v[236:237], off
	global_load_dwordx4 v[186:189], v[236:237], off offset:64
	global_load_dwordx4 v[190:193], v[236:237], off offset:512
	global_load_dwordx4 v[194:197], v[236:237], off offset:576
	v_mul_f32_e32 v55, v53, v53
	v_mul_f32_e32 v54, v51, v51
	v_fmac_f32_e32 v54, v50, v50
	v_fmac_f32_e32 v55, v52, v52
	v_add_f32_e32 v54, v54, v55
	v_add_f32_e32 v55, v58, v54
	ds_bpermute_b32 v56, v118, v55
	v_cvt_pk_bf16_f32 v246, v50, v51
	s_waitcnt lgkmcnt(0)
	v_add_f32_e32 v50, v55, v56
	ds_bpermute_b32 v51, v116, v50
	v_cvt_pk_bf16_f32 v247, v52, v53
	v_lshl_add_u64 v[52:53], s[14:15], 0, v[72:73]
	s_nop 1
	v_permlane16_swap_b32_e32 v244, v246
	v_permlane16_swap_b32_e32 v245, v247
	v_lshl_add_u64 v[250:251], v[52:53], 0, v[248:249]
	global_store_dwordx4 v[250:251], v[244:247], off offset:-32
	s_and_saveexec_b64 s[46:47], s[4:5]
	s_cbranch_execz .LBB0_247
	v_lshlrev_b64 v[52:53], 6, v[66:67]
	v_lshl_add_u64 v[52:53], s[16:17], 0, v[52:53]
	v_lshl_add_u64 v[52:53], s[38:39], 2, v[52:53]
	s_lshl_b32 s26, s59, 2
	v_lshl_add_u64 v[52:53], v[52:53], 0, s[26:27]
	s_waitcnt lgkmcnt(0)
	v_add_f32_e32 v50, v50, v51
	global_store_dword v[52:53], v50, off
.LBB0_247:
	s_or_b64 exec, exec, s[46:47]
	s_waitcnt lgkmcnt(0)
	v_lshl_add_u64 v[50:51], v[146:147], 0, s[36:37]
	v_lshlrev_b64 v[52:53], 10, v[50:51]
	v_lshl_add_u64 v[56:57], v[52:53], 0, v[144:145]
	v_lshl_add_u64 v[58:59], v[56:57], 2, s[18:19]
	s_waitcnt vmcnt(16)
	v_lshlrev_b64 v[56:57], 1, v[56:57]
	v_lshl_add_u64 v[60:61], s[14:15], 0, v[56:57]
	v_pk_fma_f32 v[54:55], v[48:49], 0.5, v[200:201] op_sel_hi:[1,0,1]
	v_pk_fma_f32 v[52:53], v[46:47], 0.5, v[198:199] op_sel_hi:[1,0,1]
	s_nop 0
	v_cvt_pk_bf16_f32 v240, v52, v53
	v_cvt_pk_bf16_f32 v241, v54, v55
	s_waitcnt vmcnt(15)
	v_or_b32_e32 v60, 32, v56
	v_mov_b32_e32 v61, v57
	v_lshl_add_u64 v[60:61], s[14:15], 0, v[60:61]
	v_mul_f32_e32 v53, v53, v53
	v_mul_f32_e32 v55, v55, v55
	v_fmac_f32_e32 v53, v52, v52
	v_fmac_f32_e32 v55, v54, v54
	v_add_f32_e32 v52, v53, v55
	v_pk_fma_f32 v[48:49], v[44:45], 0.5, v[204:205] op_sel_hi:[1,0,1]
	v_pk_fma_f32 v[46:47], v[42:43], 0.5, v[202:203] op_sel_hi:[1,0,1]
	s_nop 0
	v_cvt_pk_bf16_f32 v242, v46, v47
	v_cvt_pk_bf16_f32 v243, v48, v49
	s_nop 1
	v_permlane16_swap_b32_e32 v240, v242
	v_permlane16_swap_b32_e32 v241, v243
	v_lshl_add_u64 v[250:251], v[60:61], 0, v[248:249]
	global_store_dwordx4 v[250:251], v[240:243], off offset:-32
	s_waitcnt vmcnt(15)
	v_or_b32_e32 v60, 0x100, v56
	v_mov_b32_e32 v61, v57
	v_lshl_add_u64 v[60:61], s[14:15], 0, v[60:61]
	v_mul_f32_e32 v47, v47, v47
	v_mul_f32_e32 v49, v49, v49
	v_fmac_f32_e32 v47, v46, v46
	v_fmac_f32_e32 v49, v48, v48
	v_add_f32_e32 v46, v47, v49
	v_add_f32_e32 v46, v52, v46
	v_or_b32_e32 v56, 0x120, v56
	v_pk_fma_f32 v[44:45], v[40:41], 0.5, v[208:209] op_sel_hi:[1,0,1]
	v_pk_fma_f32 v[42:43], v[38:39], 0.5, v[206:207] op_sel_hi:[1,0,1]
	s_nop 0
	v_cvt_pk_bf16_f32 v244, v42, v43
	v_cvt_pk_bf16_f32 v245, v44, v45
	s_waitcnt vmcnt(14)
	v_mul_f32_e32 v43, v43, v43
	v_mul_f32_e32 v45, v45, v45
	v_fmac_f32_e32 v43, v42, v42
	v_fmac_f32_e32 v45, v44, v44
	v_add_f32_e32 v42, v43, v45
	v_add_f32_e32 v42, v46, v42
	v_pk_fma_f32 v[36:37], v[36:37], 0.5, v[212:213] op_sel_hi:[1,0,1]
	v_pk_fma_f32 v[34:35], v[34:35], 0.5, v[210:211] op_sel_hi:[1,0,1]
	v_mul_f32_e32 v39, v37, v37
	v_mul_f32_e32 v38, v35, v35
	v_fmac_f32_e32 v38, v34, v34
	v_fmac_f32_e32 v39, v36, v36
	v_add_f32_e32 v38, v38, v39
	v_add_f32_e32 v39, v42, v38
	ds_bpermute_b32 v40, v118, v39
	v_cvt_pk_bf16_f32 v246, v34, v35
	s_waitcnt lgkmcnt(0)
	v_add_f32_e32 v34, v39, v40
	ds_bpermute_b32 v35, v116, v34
	v_cvt_pk_bf16_f32 v247, v36, v37
	v_lshl_add_u64 v[36:37], s[14:15], 0, v[56:57]
	s_nop 1
	v_permlane16_swap_b32_e32 v244, v246
	v_permlane16_swap_b32_e32 v245, v247
	v_lshl_add_u64 v[250:251], v[36:37], 0, v[248:249]
	global_store_dwordx4 v[250:251], v[244:247], off offset:-32
	s_and_saveexec_b64 s[46:47], s[4:5]
	s_cbranch_execz .LBB0_249
	v_lshlrev_b64 v[36:37], 6, v[50:51]
	v_lshl_add_u64 v[36:37], s[16:17], 0, v[36:37]
	v_lshl_add_u64 v[36:37], s[38:39], 2, v[36:37]
	s_lshl_b32 s26, s59, 2
	v_lshl_add_u64 v[36:37], v[36:37], 0, s[26:27]
	s_waitcnt lgkmcnt(0)
	v_add_f32_e32 v34, v34, v35
	global_store_dword v[36:37], v34, off
.LBB0_249:
	s_or_b64 exec, exec, s[46:47]
	s_waitcnt lgkmcnt(0)
	v_lshl_add_u64 v[34:35], v[146:147], 0, s[40:41]
	v_lshlrev_b64 v[36:37], 10, v[34:35]
	v_lshl_add_u64 v[40:41], v[36:37], 0, v[144:145]
	v_lshl_add_u64 v[42:43], v[40:41], 2, s[18:19]
	s_waitcnt vmcnt(12)
	v_lshlrev_b64 v[40:41], 1, v[40:41]
	v_lshl_add_u64 v[44:45], s[14:15], 0, v[40:41]
	v_pk_fma_f32 v[38:39], v[32:33], 0.5, v[168:169] op_sel_hi:[1,0,1]
	v_pk_fma_f32 v[36:37], v[30:31], 0.5, v[166:167] op_sel_hi:[1,0,1]
	s_nop 0
	v_cvt_pk_bf16_f32 v240, v36, v37
	v_cvt_pk_bf16_f32 v241, v38, v39
	s_waitcnt vmcnt(11)
	v_or_b32_e32 v44, 32, v40
	v_mov_b32_e32 v45, v41
	v_lshl_add_u64 v[44:45], s[14:15], 0, v[44:45]
	v_mul_f32_e32 v37, v37, v37
	v_mul_f32_e32 v39, v39, v39
	v_fmac_f32_e32 v37, v36, v36
	v_fmac_f32_e32 v39, v38, v38
	v_add_f32_e32 v36, v37, v39
	v_pk_fma_f32 v[32:33], v[28:29], 0.5, v[172:173] op_sel_hi:[1,0,1]
	v_pk_fma_f32 v[30:31], v[26:27], 0.5, v[170:171] op_sel_hi:[1,0,1]
	s_nop 0
	v_cvt_pk_bf16_f32 v242, v30, v31
	v_cvt_pk_bf16_f32 v243, v32, v33
	s_nop 1
	v_permlane16_swap_b32_e32 v240, v242
	v_permlane16_swap_b32_e32 v241, v243
	v_lshl_add_u64 v[250:251], v[44:45], 0, v[248:249]
	global_store_dwordx4 v[250:251], v[240:243], off offset:-32
	s_waitcnt vmcnt(11)
	v_or_b32_e32 v44, 0x100, v40
	v_mov_b32_e32 v45, v41
	v_lshl_add_u64 v[44:45], s[14:15], 0, v[44:45]
	v_mul_f32_e32 v31, v31, v31
	v_mul_f32_e32 v33, v33, v33
	v_fmac_f32_e32 v31, v30, v30
	v_fmac_f32_e32 v33, v32, v32
	v_add_f32_e32 v30, v31, v33
	v_add_f32_e32 v30, v36, v30
	v_or_b32_e32 v40, 0x120, v40
	v_pk_fma_f32 v[28:29], v[24:25], 0.5, v[176:177] op_sel_hi:[1,0,1]
	v_pk_fma_f32 v[26:27], v[22:23], 0.5, v[174:175] op_sel_hi:[1,0,1]
	s_nop 0
	v_cvt_pk_bf16_f32 v244, v26, v27
	v_cvt_pk_bf16_f32 v245, v28, v29
	s_waitcnt vmcnt(10)
	v_mul_f32_e32 v27, v27, v27
	v_mul_f32_e32 v29, v29, v29
	v_fmac_f32_e32 v27, v26, v26
	v_fmac_f32_e32 v29, v28, v28
	v_add_f32_e32 v26, v27, v29
	v_add_f32_e32 v26, v30, v26
	v_pk_fma_f32 v[20:21], v[20:21], 0.5, v[180:181] op_sel_hi:[1,0,1]
	v_pk_fma_f32 v[18:19], v[18:19], 0.5, v[178:179] op_sel_hi:[1,0,1]
	v_mul_f32_e32 v23, v21, v21
	v_mul_f32_e32 v22, v19, v19
	v_fmac_f32_e32 v22, v18, v18
	v_fmac_f32_e32 v23, v20, v20
	v_add_f32_e32 v22, v22, v23
	v_add_f32_e32 v23, v26, v22
	ds_bpermute_b32 v24, v118, v23
	v_cvt_pk_bf16_f32 v246, v18, v19
	s_waitcnt lgkmcnt(0)
	v_add_f32_e32 v18, v23, v24
	ds_bpermute_b32 v19, v116, v18
	v_cvt_pk_bf16_f32 v247, v20, v21
	v_lshl_add_u64 v[20:21], s[14:15], 0, v[40:41]
	s_nop 1
	v_permlane16_swap_b32_e32 v244, v246
	v_permlane16_swap_b32_e32 v245, v247
	v_lshl_add_u64 v[250:251], v[20:21], 0, v[248:249]
	global_store_dwordx4 v[250:251], v[244:247], off offset:-32
	s_and_saveexec_b64 s[46:47], s[4:5]
	s_cbranch_execz .LBB0_251
	v_lshlrev_b64 v[20:21], 6, v[34:35]
	v_lshl_add_u64 v[20:21], s[16:17], 0, v[20:21]
	v_lshl_add_u64 v[20:21], s[38:39], 2, v[20:21]
	s_lshl_b32 s26, s59, 2
	v_lshl_add_u64 v[20:21], v[20:21], 0, s[26:27]
	s_waitcnt lgkmcnt(0)
	v_add_f32_e32 v18, v18, v19
	global_store_dword v[20:21], v18, off
.LBB0_251:
	s_or_b64 exec, exec, s[46:47]
	s_waitcnt lgkmcnt(0)
	v_lshl_add_u64 v[18:19], v[146:147], 0, s[42:43]
	v_lshlrev_b64 v[20:21], 10, v[18:19]
	v_lshl_add_u64 v[24:25], v[20:21], 0, v[144:145]
	v_lshl_add_u64 v[26:27], v[24:25], 2, s[18:19]
	s_waitcnt vmcnt(8)
	v_lshlrev_b64 v[24:25], 1, v[24:25]
	v_lshl_add_u64 v[28:29], s[14:15], 0, v[24:25]
	v_pk_fma_f32 v[22:23], v[16:17], 0.5, v[184:185] op_sel_hi:[1,0,1]
	v_pk_fma_f32 v[20:21], v[14:15], 0.5, v[182:183] op_sel_hi:[1,0,1]
	s_nop 0
	v_cvt_pk_bf16_f32 v240, v20, v21
	v_cvt_pk_bf16_f32 v241, v22, v23
	s_waitcnt vmcnt(7)
	v_or_b32_e32 v28, 32, v24
	v_mov_b32_e32 v29, v25
	v_lshl_add_u64 v[28:29], s[14:15], 0, v[28:29]
	v_mul_f32_e32 v21, v21, v21
	v_mul_f32_e32 v23, v23, v23
	v_fmac_f32_e32 v21, v20, v20
	v_fmac_f32_e32 v23, v22, v22
	v_add_f32_e32 v20, v21, v23
	v_pk_fma_f32 v[16:17], v[12:13], 0.5, v[188:189] op_sel_hi:[1,0,1]
	v_pk_fma_f32 v[14:15], v[10:11], 0.5, v[186:187] op_sel_hi:[1,0,1]
	s_nop 0
	v_cvt_pk_bf16_f32 v242, v14, v15
	v_cvt_pk_bf16_f32 v243, v16, v17
	s_nop 1
	v_permlane16_swap_b32_e32 v240, v242
	v_permlane16_swap_b32_e32 v241, v243
	v_lshl_add_u64 v[250:251], v[28:29], 0, v[248:249]
	global_store_dwordx4 v[250:251], v[240:243], off offset:-32
	s_waitcnt vmcnt(7)
	v_or_b32_e32 v28, 0x100, v24
	v_mov_b32_e32 v29, v25
	v_lshl_add_u64 v[28:29], s[14:15], 0, v[28:29]
	v_mul_f32_e32 v15, v15, v15
	v_mul_f32_e32 v17, v17, v17
	v_fmac_f32_e32 v15, v14, v14
	v_fmac_f32_e32 v17, v16, v16
	v_add_f32_e32 v14, v15, v17
	v_add_f32_e32 v14, v20, v14
	v_or_b32_e32 v24, 0x120, v24
	v_pk_fma_f32 v[12:13], v[8:9], 0.5, v[192:193] op_sel_hi:[1,0,1]
	v_pk_fma_f32 v[10:11], v[6:7], 0.5, v[190:191] op_sel_hi:[1,0,1]
	s_nop 0
	v_cvt_pk_bf16_f32 v244, v10, v11
	v_cvt_pk_bf16_f32 v245, v12, v13
	s_waitcnt vmcnt(6)
	v_mul_f32_e32 v11, v11, v11
	v_mul_f32_e32 v13, v13, v13
	v_fmac_f32_e32 v11, v10, v10
	v_fmac_f32_e32 v13, v12, v12
	v_add_f32_e32 v10, v11, v13
	v_add_f32_e32 v10, v14, v10
	v_pk_fma_f32 v[4:5], v[4:5], 0.5, v[196:197] op_sel_hi:[1,0,1]
	v_pk_fma_f32 v[2:3], v[2:3], 0.5, v[194:195] op_sel_hi:[1,0,1]
	v_mul_f32_e32 v7, v5, v5
	v_mul_f32_e32 v6, v3, v3
	v_fmac_f32_e32 v6, v2, v2
	v_fmac_f32_e32 v7, v4, v4
	v_add_f32_e32 v6, v6, v7
	v_add_f32_e32 v7, v10, v6
	ds_bpermute_b32 v8, v118, v7
	v_cvt_pk_bf16_f32 v246, v2, v3
	s_waitcnt lgkmcnt(0)
	v_add_f32_e32 v2, v7, v8
	ds_bpermute_b32 v3, v116, v2
	v_cvt_pk_bf16_f32 v247, v4, v5
	v_lshl_add_u64 v[4:5], s[14:15], 0, v[24:25]
	s_nop 1
	v_permlane16_swap_b32_e32 v244, v246
	v_permlane16_swap_b32_e32 v245, v247
	v_lshl_add_u64 v[250:251], v[4:5], 0, v[248:249]
	global_store_dwordx4 v[250:251], v[244:247], off offset:-32
	s_and_saveexec_b64 s[46:47], s[4:5]
	s_cbranch_execz .LBB0_253
	v_lshlrev_b64 v[4:5], 6, v[18:19]
	v_lshl_add_u64 v[4:5], s[16:17], 0, v[4:5]
	v_lshl_add_u64 v[4:5], s[38:39], 2, v[4:5]
	s_lshl_b32 s26, s59, 2
	v_lshl_add_u64 v[4:5], v[4:5], 0, s[26:27]
	s_waitcnt lgkmcnt(0)
	v_add_f32_e32 v2, v2, v3
	global_store_dword v[4:5], v2, off
